# GQA attention loop back to one barrier per KV tile (no half-tile offset between wave halves), hoisted staging addresses kept; otherwise v29
# speedup vs baseline: 1.0139x; 1.0139x over previous
; template <int DK, int DV, int MODE, int QB, bool PACK = false>
; DI void attn_item(const AttArgs& a, int q0, int t_lo, int t_hi) {
;     ...
;   u32x4 kr[NKL], vr[NVL];
;   att_gload<DK, DV, MODE>(a, t_lo, kr, vr);
;   att_swrite<DK, DV>(0, kr, vr);
;   if (t_lo + 1 < t_hi) att_gload<DK, DV, MODE>(a, t_lo + 1, kr, vr);
;   __syncthreads();
;   const float scale = a.scale;
;   const float cexp = (MODE == 2) ? LOG2E : a.scale * LOG2E;
;   const int vq = (l & 15) >> 2, vp = l & 3, vblk = (l >> 4) & 1;
;   for (int tile = t_lo; tile < t_hi; ++tile) {
;     const int buf = (tile - t_lo) & 1;
;     if (tile + 1 < t_hi) att_swrite<DK, DV>(buf ^ 1, kr, vr);
;     if (tile + 2 < t_hi) att_gload<DK, DV, MODE>(a, tile + 2, kr, vr);
.LBB0_834:
	s_or_b64 exec, exec, s[4:5]
	s_waitcnt vmcnt(1)
	v_add_u32_e32 v8, v12, v14
	s_waitcnt vmcnt(0)
	ds_write_b128 v8, v[4:7] offset:9216
	v_mov_b32_e32 v8, v224
	s_mov_b32 s4, 0x40000
	v_min_i32_e32 v5, 0x1ff, v8
	v_ashrrev_i32_e32 v4, 31, v5
	v_lshrrev_b32_e32 v4, 29, v4
	v_add_u32_e32 v6, v5, v4
	v_ashrrev_i32_e32 v4, 3, v6
	v_and_b32_e32 v6, 0x1ffffff8, v6
	v_sub_u32_e32 v6, v5, v6
	v_ashrrev_i32_e32 v5, 31, v4
	v_lshlrev_b64 v[4:5], 12, v[4:5]
	v_lshlrev_b32_e32 v6, 3, v6
	v_ashrrev_i32_e32 v7, 31, v6
	v_lshl_add_u64 v[4:5], s[2:3], 0, v[4:5]
	v_lshl_add_u64 v[4:5], v[6:7], 1, v[4:5]
	v_ashrrev_i32_e32 v6, 31, v8
	v_lshrrev_b32_e32 v6, 29, v6
	v_add_u32_e32 v7, v8, v6
	v_ashrrev_i32_e32 v6, 3, v7
	v_and_b32_e32 v7, 0x1ffffff8, v7
	v_sub_u32_e32 v8, v8, v7
	v_ashrrev_i32_e32 v7, 31, v6
	v_lshlrev_b64 v[6:7], 12, v[6:7]
	v_lshlrev_b32_e32 v8, 3, v8
	v_add_co_u32_e32 v4, vcc, s4, v4
	v_ashrrev_i32_e32 v9, 31, v8
	v_lshl_add_u64 v[6:7], s[2:3], 0, v[6:7]
	v_addc_co_u32_e32 v5, vcc, 0, v5, vcc
	v_lshl_add_u64 v[6:7], v[8:9], 1, v[6:7]
	v_add_co_u32_e32 v6, vcc, s4, v6
	v_lshlrev_b32_e32 v189, 3, v3
	s_nop 0
	v_addc_co_u32_e32 v7, vcc, 0, v7, vcc
	global_load_dwordx4 v[176:179], v[4:5], off offset:1024
	global_load_dwordx4 v[180:183], v[6:7], off offset:1280
	v_bfe_u32 v4, v1, 2, 2
	v_and_b32_e32 v5, 16, v1
	v_lshlrev_b32_e32 v1, 2, v1
	v_lshl_or_b32 v3, v3, 2, v4
	v_and_or_b32 v1, v1, 12, v5
	v_mov_b32_e32 v14, v2
	v_mov_b32_e32 v15, v2
	v_lshlrev_b32_e32 v204, 1, v1
	v_mul_u32_u24_e32 v208, 0x90, v0
	v_mul_u32_u24_e32 v205, 0x90, v3
	v_mov_b32_e32 v0, v2
	v_mov_b32_e32 v1, v2
	v_mov_b32_e32 v3, v2
	v_mov_b32_e32 v4, v2
	v_mov_b32_e32 v5, v2
	v_mov_b32_e32 v6, v2
	v_mov_b32_e32 v7, v2
	v_mov_b32_e32 v8, v2
	v_mov_b32_e32 v9, v2
	v_mov_b32_e32 v10, v2
	v_mov_b32_e32 v11, v2
	v_mov_b32_e32 v12, v2
	v_mov_b32_e32 v13, v2
	v_mov_b64_e32 v[30:31], v[14:15]
	v_mov_b64_e32 v[46:47], v[14:15]
	v_mov_b64_e32 v[62:63], v[14:15]
	v_mov_b64_e32 v[78:79], v[14:15]
	s_lshl_b32 s8, s6, 6
	s_mov_b32 s9, 0
	v_mov_b32_e32 v206, 0
	v_mov_b32_e32 v191, 0xf149f2ca
	s_add_u32 s4, s2, 0x80000
	s_addc_u32 s5, s3, 0
	v_lshrrev_b32_e32 v210, 3, v224
	v_and_b32_e32 v211, 7, v224
	v_lshlrev_b32_e32 v212, 12, v210
	v_lshl_or_b32 v212, v211, 4, v212
	v_mul_u32_u24_e32 v210, 0x90, v210
	v_lshl_add_u32 v210, v211, 4, v210
	v_mov_b64_e32 v[28:29], v[12:13]
	v_mov_b64_e32 v[26:27], v[10:11]
	v_mov_b64_e32 v[24:25], v[8:9]
	v_mov_b64_e32 v[22:23], v[6:7]
	v_mov_b64_e32 v[20:21], v[4:5]
	v_mov_b64_e32 v[18:19], v[2:3]
	v_mov_b64_e32 v[16:17], v[0:1]
	v_mov_b64_e32 v[44:45], v[12:13]
	v_mov_b64_e32 v[42:43], v[10:11]
	v_mov_b64_e32 v[40:41], v[8:9]
	v_mov_b64_e32 v[38:39], v[6:7]
	v_mov_b64_e32 v[36:37], v[4:5]
	v_mov_b64_e32 v[34:35], v[2:3]
	v_mov_b64_e32 v[32:33], v[0:1]
	v_mov_b64_e32 v[60:61], v[12:13]
	v_mov_b64_e32 v[58:59], v[10:11]
	v_mov_b64_e32 v[56:57], v[8:9]
	v_mov_b64_e32 v[54:55], v[6:7]
	v_mov_b64_e32 v[52:53], v[4:5]
	v_mov_b64_e32 v[50:51], v[2:3]
	v_mov_b64_e32 v[48:49], v[0:1]
	v_mov_b64_e32 v[76:77], v[12:13]
	v_mov_b64_e32 v[74:75], v[10:11]
	v_mov_b64_e32 v[72:73], v[8:9]
	v_mov_b64_e32 v[70:71], v[6:7]
	v_mov_b64_e32 v[68:69], v[4:5]
	v_mov_b64_e32 v[66:67], v[2:3]
	v_mov_b64_e32 v[64:65], v[0:1]
	v_mov_b32_e32 v1, 0xf149f2ca
	v_mov_b32_e32 v207, 0
	s_waitcnt lgkmcnt(0)
	s_barrier
	s_branch .LBB0_836
.LBB0_835:
	s_cmp_gt_u32 s9, 29
	s_cbranch_scc1 .Lpp0_last
	s_waitcnt vmcnt(1)
	ds_write_b128 v211, v[180:183] offset:9216
	global_load_dwordx4 v[180:183], v212, s[4:5] offset:1280
	s_branch .Lpp0_cont
